# v12 plus merge epilogue loops unrolled x4 with all gate and partial loads issued ahead of the LDS barrier (counted vmcnt waits)
# speedup vs baseline: 1.0301x; 1.0078x over previous
.LBB0_320:
	s_or_b64 exec, exec, s[24:25]
	v_lshl_add_u32 v140, s44, 7, v175
	v_ashrrev_i32_e32 v141, 31, v140
	v_mad_i64_i32 v[138:139], s[24:25], v140, s38, 0
	v_mad_i64_i32 v[142:143], s[24:25], v140, s38, v[130:131]
	v_lshlrev_b64 v[140:141], 11, v[140:141]
	s_xor_b64 s[22:23], s[22:23], -1
	v_lshl_add_u64 v[144:145], v[132:133], 0, v[140:141]
	s_mov_b32 s24, 0
	global_load_dwordx4 v[198:201], v[142:143], off offset:-8
	v_lshl_add_u64 v[142:143], v[142:143], 0, s[14:15]
	global_load_dwordx4 v[202:205], v[142:143], off offset:-8
	v_lshl_add_u64 v[142:143], v[142:143], 0, s[14:15]
	global_load_dwordx4 v[206:209], v[142:143], off offset:-8
	v_lshl_add_u64 v[142:143], v[142:143], 0, s[14:15]
	global_load_dwordx4 v[210:213], v[142:143], off offset:-8
	v_lshl_add_u64 v[142:143], v[142:143], 0, s[14:15]
	s_waitcnt lgkmcnt(0)
	s_barrier
.LBB0_321:
	v_add_u32_e32 v176, s24, v174
	ds_read_b128 v[190:193], v176
	ds_read_b128 v[194:197], v176 offset:16
	s_add_i32 s24, s24, 0x8200
	s_cmp_lg_u32 s24, 0x20800
	s_waitcnt vmcnt(3)
	v_lshlrev_b32_e32 v176, 16, v198
	v_and_b32_e32 v177, 0xffff0000, v198
	v_lshlrev_b32_e32 v180, 16, v199
	v_and_b32_e32 v181, 0xffff0000, v199
	v_lshlrev_b32_e32 v186, 16, v200
	v_and_b32_e32 v187, 0xffff0000, v200
	v_lshlrev_b32_e32 v188, 16, v201
	v_and_b32_e32 v189, 0xffff0000, v201
	s_waitcnt lgkmcnt(1)
	v_pk_mul_f32 v[176:177], v[190:191], v[176:177]
	v_pk_mul_f32 v[180:181], v[192:193], v[180:181]
	s_waitcnt lgkmcnt(0)
	v_pk_mul_f32 v[190:191], v[194:195], v[186:187]
	v_pk_mul_f32 v[192:193], v[196:197], v[188:189]
	v_cvt_pk_bf16_f32 v186, v176, v177
	v_cvt_pk_bf16_f32 v187, v180, v181
	v_cvt_pk_bf16_f32 v188, v190, v191
	v_cvt_pk_bf16_f32 v189, v192, v193
	global_store_dwordx4 v[144:145], v[186:189], off offset:-8
	v_lshl_add_u64 v[144:145], v[144:145], 0, s[16:17]
	v_add_u32_e32 v176, s24, v174
	ds_read_b128 v[190:193], v176
	ds_read_b128 v[194:197], v176 offset:16
	s_add_i32 s24, s24, 0x8200
	s_cmp_lg_u32 s24, 0x20800
	s_waitcnt vmcnt(3)
	v_lshlrev_b32_e32 v176, 16, v202
	v_and_b32_e32 v177, 0xffff0000, v202
	v_lshlrev_b32_e32 v180, 16, v203
	v_and_b32_e32 v181, 0xffff0000, v203
	v_lshlrev_b32_e32 v186, 16, v204
	v_and_b32_e32 v187, 0xffff0000, v204
	v_lshlrev_b32_e32 v188, 16, v205
	v_and_b32_e32 v189, 0xffff0000, v205
	s_waitcnt lgkmcnt(1)
	v_pk_mul_f32 v[176:177], v[190:191], v[176:177]
	v_pk_mul_f32 v[180:181], v[192:193], v[180:181]
	s_waitcnt lgkmcnt(0)
	v_pk_mul_f32 v[190:191], v[194:195], v[186:187]
	v_pk_mul_f32 v[192:193], v[196:197], v[188:189]
	v_cvt_pk_bf16_f32 v186, v176, v177
	v_cvt_pk_bf16_f32 v187, v180, v181
	v_cvt_pk_bf16_f32 v188, v190, v191
	v_cvt_pk_bf16_f32 v189, v192, v193
	global_store_dwordx4 v[144:145], v[186:189], off offset:-8
	v_lshl_add_u64 v[144:145], v[144:145], 0, s[16:17]
	v_add_u32_e32 v176, s24, v174
	ds_read_b128 v[190:193], v176
	ds_read_b128 v[194:197], v176 offset:16
	s_add_i32 s24, s24, 0x8200
	s_cmp_lg_u32 s24, 0x20800
	s_waitcnt vmcnt(3)
	v_lshlrev_b32_e32 v176, 16, v206
	v_and_b32_e32 v177, 0xffff0000, v206
	v_lshlrev_b32_e32 v180, 16, v207
	v_and_b32_e32 v181, 0xffff0000, v207
	v_lshlrev_b32_e32 v186, 16, v208
	v_and_b32_e32 v187, 0xffff0000, v208
	v_lshlrev_b32_e32 v188, 16, v209
	v_and_b32_e32 v189, 0xffff0000, v209
	s_waitcnt lgkmcnt(1)
	v_pk_mul_f32 v[176:177], v[190:191], v[176:177]
	v_pk_mul_f32 v[180:181], v[192:193], v[180:181]
	s_waitcnt lgkmcnt(0)
	v_pk_mul_f32 v[190:191], v[194:195], v[186:187]
	v_pk_mul_f32 v[192:193], v[196:197], v[188:189]
	v_cvt_pk_bf16_f32 v186, v176, v177
	v_cvt_pk_bf16_f32 v187, v180, v181
	v_cvt_pk_bf16_f32 v188, v190, v191
	v_cvt_pk_bf16_f32 v189, v192, v193
	global_store_dwordx4 v[144:145], v[186:189], off offset:-8
	v_lshl_add_u64 v[144:145], v[144:145], 0, s[16:17]
	v_add_u32_e32 v176, s24, v174
	ds_read_b128 v[190:193], v176
	ds_read_b128 v[194:197], v176 offset:16
	s_add_i32 s24, s24, 0x8200
	s_cmp_lg_u32 s24, 0x20800
	s_waitcnt vmcnt(3)
	v_lshlrev_b32_e32 v176, 16, v210
	v_and_b32_e32 v177, 0xffff0000, v210
	v_lshlrev_b32_e32 v180, 16, v211
	v_and_b32_e32 v181, 0xffff0000, v211
	v_lshlrev_b32_e32 v186, 16, v212
	v_and_b32_e32 v187, 0xffff0000, v212
	v_lshlrev_b32_e32 v188, 16, v213
	v_and_b32_e32 v189, 0xffff0000, v213
	s_waitcnt lgkmcnt(1)
	v_pk_mul_f32 v[176:177], v[190:191], v[176:177]
	v_pk_mul_f32 v[180:181], v[192:193], v[180:181]
	s_waitcnt lgkmcnt(0)
	v_pk_mul_f32 v[190:191], v[194:195], v[186:187]
	v_pk_mul_f32 v[192:193], v[196:197], v[188:189]
	v_cvt_pk_bf16_f32 v186, v176, v177
	v_cvt_pk_bf16_f32 v187, v180, v181
	v_cvt_pk_bf16_f32 v188, v190, v191
	v_cvt_pk_bf16_f32 v189, v192, v193
	global_store_dwordx4 v[144:145], v[186:189], off offset:-8
	v_lshl_add_u64 v[144:145], v[144:145], 0, s[16:17]
	v_lshl_add_u64 v[138:139], v[134:135], 0, v[138:139]
	v_lshl_add_u64 v[140:141], v[136:137], 0, v[140:141]
	s_movk_i32 s24, 0x200
	global_load_dwordx4 v[198:201], v[138:139], off offset:-8
	v_lshl_add_u64 v[138:139], v[138:139], 0, s[14:15]
	global_load_dwordx4 v[202:205], v[138:139], off offset:-8
	v_lshl_add_u64 v[138:139], v[138:139], 0, s[14:15]
	global_load_dwordx4 v[206:209], v[138:139], off offset:-8
	v_lshl_add_u64 v[138:139], v[138:139], 0, s[14:15]
	global_load_dwordx4 v[210:213], v[138:139], off offset:-8
	v_lshl_add_u64 v[138:139], v[138:139], 0, s[14:15]
.LBB0_323:
	v_add_u32_e32 v176, s24, v174
	ds_read_b128 v[186:189], v176
	ds_read_b128 v[190:193], v176 offset:16
	s_add_i32 s24, s24, 0x8200
	s_cmp_lg_u32 s24, 0x20a00
	s_waitcnt vmcnt(3)
	v_lshlrev_b32_e32 v176, 16, v198
	v_and_b32_e32 v177, 0xffff0000, v198
	v_lshlrev_b32_e32 v142, 16, v199
	v_and_b32_e32 v143, 0xffff0000, v199
	v_lshlrev_b32_e32 v180, 16, v200
	v_and_b32_e32 v181, 0xffff0000, v200
	v_lshlrev_b32_e32 v144, 16, v201
	v_and_b32_e32 v145, 0xffff0000, v201
	s_waitcnt lgkmcnt(1)
	v_pk_mul_f32 v[176:177], v[186:187], v[176:177]
	v_pk_mul_f32 v[186:187], v[188:189], v[142:143]
	s_waitcnt lgkmcnt(0)
	v_pk_mul_f32 v[180:181], v[190:191], v[180:181]
	v_pk_mul_f32 v[188:189], v[192:193], v[144:145]
	v_cvt_pk_bf16_f32 v142, v176, v177
	v_cvt_pk_bf16_f32 v143, v186, v187
	v_cvt_pk_bf16_f32 v144, v180, v181
	v_cvt_pk_bf16_f32 v145, v188, v189
	global_store_dwordx4 v[140:141], v[142:145], off offset:-8
	v_lshl_add_u64 v[140:141], v[140:141], 0, s[16:17]
	v_add_u32_e32 v176, s24, v174
	ds_read_b128 v[186:189], v176
	ds_read_b128 v[190:193], v176 offset:16
	s_add_i32 s24, s24, 0x8200
	s_cmp_lg_u32 s24, 0x20a00
	s_waitcnt vmcnt(3)
	v_lshlrev_b32_e32 v176, 16, v202
	v_and_b32_e32 v177, 0xffff0000, v202
	v_lshlrev_b32_e32 v142, 16, v203
	v_and_b32_e32 v143, 0xffff0000, v203
	v_lshlrev_b32_e32 v180, 16, v204
	v_and_b32_e32 v181, 0xffff0000, v204
	v_lshlrev_b32_e32 v144, 16, v205
	v_and_b32_e32 v145, 0xffff0000, v205
	s_waitcnt lgkmcnt(1)
	v_pk_mul_f32 v[176:177], v[186:187], v[176:177]
	v_pk_mul_f32 v[186:187], v[188:189], v[142:143]
	s_waitcnt lgkmcnt(0)
	v_pk_mul_f32 v[180:181], v[190:191], v[180:181]
	v_pk_mul_f32 v[188:189], v[192:193], v[144:145]
	v_cvt_pk_bf16_f32 v142, v176, v177
	v_cvt_pk_bf16_f32 v143, v186, v187
	v_cvt_pk_bf16_f32 v144, v180, v181
	v_cvt_pk_bf16_f32 v145, v188, v189
	global_store_dwordx4 v[140:141], v[142:145], off offset:-8
	v_lshl_add_u64 v[140:141], v[140:141], 0, s[16:17]
	v_add_u32_e32 v176, s24, v174
	ds_read_b128 v[186:189], v176
	ds_read_b128 v[190:193], v176 offset:16
	s_add_i32 s24, s24, 0x8200
	s_cmp_lg_u32 s24, 0x20a00
	s_waitcnt vmcnt(3)
	v_lshlrev_b32_e32 v176, 16, v206
	v_and_b32_e32 v177, 0xffff0000, v206
	v_lshlrev_b32_e32 v142, 16, v207
	v_and_b32_e32 v143, 0xffff0000, v207
	v_lshlrev_b32_e32 v180, 16, v208
	v_and_b32_e32 v181, 0xffff0000, v208
	v_lshlrev_b32_e32 v144, 16, v209
	v_and_b32_e32 v145, 0xffff0000, v209
	s_waitcnt lgkmcnt(1)
	v_pk_mul_f32 v[176:177], v[186:187], v[176:177]
	v_pk_mul_f32 v[186:187], v[188:189], v[142:143]
	s_waitcnt lgkmcnt(0)
	v_pk_mul_f32 v[180:181], v[190:191], v[180:181]
	v_pk_mul_f32 v[188:189], v[192:193], v[144:145]
	v_cvt_pk_bf16_f32 v142, v176, v177
	v_cvt_pk_bf16_f32 v143, v186, v187
	v_cvt_pk_bf16_f32 v144, v180, v181
	v_cvt_pk_bf16_f32 v145, v188, v189
	global_store_dwordx4 v[140:141], v[142:145], off offset:-8
	v_lshl_add_u64 v[140:141], v[140:141], 0, s[16:17]
	v_add_u32_e32 v176, s24, v174
	ds_read_b128 v[186:189], v176
	ds_read_b128 v[190:193], v176 offset:16
	s_add_i32 s24, s24, 0x8200
	s_cmp_lg_u32 s24, 0x20a00
	s_waitcnt vmcnt(3)
	v_lshlrev_b32_e32 v176, 16, v210
	v_and_b32_e32 v177, 0xffff0000, v210
	v_lshlrev_b32_e32 v142, 16, v211
	v_and_b32_e32 v143, 0xffff0000, v211
	v_lshlrev_b32_e32 v180, 16, v212
	v_and_b32_e32 v181, 0xffff0000, v212
	v_lshlrev_b32_e32 v144, 16, v213
	v_and_b32_e32 v145, 0xffff0000, v213
	s_waitcnt lgkmcnt(1)
	v_pk_mul_f32 v[176:177], v[186:187], v[176:177]
	v_pk_mul_f32 v[186:187], v[188:189], v[142:143]
	s_waitcnt lgkmcnt(0)
	v_pk_mul_f32 v[180:181], v[190:191], v[180:181]
	v_pk_mul_f32 v[188:189], v[192:193], v[144:145]
	v_cvt_pk_bf16_f32 v142, v176, v177
	v_cvt_pk_bf16_f32 v143, v186, v187
	v_cvt_pk_bf16_f32 v144, v180, v181
	v_cvt_pk_bf16_f32 v145, v188, v189
	global_store_dwordx4 v[140:141], v[142:145], off offset:-8
	v_lshl_add_u64 v[140:141], v[140:141], 0, s[16:17]
	s_mov_b32 s44, 1
	s_andn2_b64 vcc, exec, s[22:23]
	s_mov_b64 s[22:23], 0
	s_cbranch_vccnz .LBB0_318
	s_lshl_b32 s22, s43, 1
	s_add_u32 s24, s33, s22
	s_addc_u32 s25, s34, 0
	s_lshl_b64 s[20:21], s[20:21], 1
	s_add_u32 s43, s30, s20
	v_readfirstlane_b32 s20, v146
	s_addc_u32 s44, s31, s21
	s_ashr_i32 s45, s20, 6
	s_lshl_b32 s20, s45, 5
	s_ashr_i32 s21, s20, 31
	s_lshl_b64 s[22:23], s[20:21], 11
	s_add_u32 s22, s24, s22
	s_addc_u32 s23, s25, s23
	s_lshl_b64 s[20:21], s[20:21], 10
	s_add_u32 s20, s43, s20
	s_addc_u32 s21, s44, s21
	s_lshl_b32 s24, s45, 12
	s_add_i32 s25, s24, 0x8000
	s_add_u32 s44, s22, 0x4000
	s_barrier
	s_mov_b32 m0, s24
	global_load_lds_dwordx4 v147, s[22:23]
	s_addc_u32 s45, s23, 0
	s_or_b32 s43, s24, 0x400
	s_mov_b32 m0, s43
	global_load_lds_dwordx4 v148, s[44:45]
	s_add_u32 s44, s22, 0x8000
	s_addc_u32 s45, s23, 0
	s_or_b32 s43, s24, 0x800
	s_mov_b32 m0, s43
	global_load_lds_dwordx4 v147, s[44:45]
	s_add_u32 s44, s22, 0xc000
	s_addc_u32 s45, s23, 0
	s_or_b32 s43, s24, 0xc00
	s_mov_b32 m0, s43
	global_load_lds_dwordx4 v148, s[44:45]
	s_add_u32 s44, s20, 0x2000
	s_mov_b32 m0, s25
	global_load_lds_dwordx4 v149, s[20:21]
	s_addc_u32 s45, s21, 0
	s_add_i32 s25, s24, 0x8400
	s_mov_b32 m0, s25
	global_load_lds_dwordx4 v150, s[44:45]
	s_add_u32 s44, s20, 0x4000
	s_addc_u32 s45, s21, 0
	s_add_i32 s25, s24, 0x8800
	s_mov_b32 m0, s25
	global_load_lds_dwordx4 v149, s[44:45]
	s_add_u32 s44, s20, 0x6000
	s_addc_u32 s45, s21, 0
	s_add_i32 s25, s24, 0x8c00
	s_mov_b32 m0, s25
	global_load_lds_dwordx4 v150, s[44:45]
	s_add_u32 s25, s20, 0x6080
	s_addc_u32 s43, s21, 0
	s_add_u32 s44, s20, 0x4080
	s_addc_u32 s45, s21, 0
	s_add_u32 s46, s20, 0x2080
	s_addc_u32 s47, s21, 0
	s_add_u32 s48, s20, 0x80
	s_addc_u32 s49, s21, 0
	s_add_u32 s50, s22, 0xc080
	s_addc_u32 s51, s23, 0
	s_add_u32 s52, s22, 0x8080
	s_addc_u32 s53, s23, 0
	s_add_u32 s54, s22, 0x4080
	s_addc_u32 s55, s23, 0
	s_add_u32 s56, s22, 0x80
	v_mov_b32_e32 v0, 0
	s_addc_u32 s57, s23, 0
	s_mov_b32 s59, 0
	s_mov_b64 s[20:21], 0
	s_mov_b32 s58, 0
	v_mov_b32_e32 v1, v0
	v_mov_b32_e32 v2, v0
	v_mov_b32_e32 v3, v0
	v_mov_b32_e32 v4, v0
	v_mov_b32_e32 v5, v0
	v_mov_b32_e32 v6, v0
	v_mov_b32_e32 v7, v0
	v_mov_b32_e32 v8, v0
	v_mov_b32_e32 v9, v0
	v_mov_b32_e32 v10, v0
	v_mov_b32_e32 v11, v0
	v_mov_b32_e32 v12, v0
	v_mov_b32_e32 v13, v0
	v_mov_b32_e32 v14, v0
	v_mov_b32_e32 v15, v0
	v_mov_b32_e32 v16, v0
	v_mov_b32_e32 v17, v0
	v_mov_b32_e32 v18, v0
	v_mov_b32_e32 v19, v0
	v_mov_b32_e32 v20, v0
	v_mov_b32_e32 v21, v0
	v_mov_b32_e32 v22, v0
	v_mov_b32_e32 v23, v0
	v_mov_b32_e32 v24, v0
	v_mov_b32_e32 v25, v0
	v_mov_b32_e32 v26, v0
	v_mov_b32_e32 v27, v0
	v_mov_b32_e32 v28, v0
	v_mov_b32_e32 v29, v0
	v_mov_b32_e32 v30, v0
	v_mov_b32_e32 v31, v0
	v_mov_b32_e32 v32, v0
	v_mov_b32_e32 v33, v0
	v_mov_b32_e32 v34, v0
	v_mov_b32_e32 v35, v0
	v_mov_b32_e32 v36, v0
	v_mov_b32_e32 v37, v0
	v_mov_b32_e32 v38, v0
	v_mov_b32_e32 v39, v0
	v_mov_b32_e32 v40, v0
	v_mov_b32_e32 v41, v0
	v_mov_b32_e32 v42, v0
	v_mov_b32_e32 v43, v0
	v_mov_b32_e32 v44, v0
	v_mov_b32_e32 v45, v0
	v_mov_b32_e32 v46, v0
	v_mov_b32_e32 v47, v0
	v_mov_b32_e32 v48, v0
	v_mov_b32_e32 v49, v0
	v_mov_b32_e32 v50, v0
	v_mov_b32_e32 v51, v0
	v_mov_b32_e32 v52, v0
	v_mov_b32_e32 v53, v0
	v_mov_b32_e32 v54, v0
	v_mov_b32_e32 v55, v0
	v_mov_b32_e32 v56, v0
	v_mov_b32_e32 v57, v0
	v_mov_b32_e32 v58, v0
	v_mov_b32_e32 v59, v0
	v_mov_b32_e32 v60, v0
	v_mov_b32_e32 v61, v0
	v_mov_b32_e32 v62, v0
	v_mov_b32_e32 v63, v0
	v_mov_b32_e32 v64, v0
	v_mov_b32_e32 v65, v0
	v_mov_b32_e32 v66, v0
	v_mov_b32_e32 v67, v0
	v_mov_b32_e32 v68, v0
	v_mov_b32_e32 v69, v0
	v_mov_b32_e32 v70, v0
	v_mov_b32_e32 v71, v0
	v_mov_b32_e32 v72, v0
	v_mov_b32_e32 v73, v0
	v_mov_b32_e32 v74, v0
	v_mov_b32_e32 v75, v0
	v_mov_b32_e32 v76, v0
	v_mov_b32_e32 v77, v0
	v_mov_b32_e32 v78, v0
	v_mov_b32_e32 v79, v0
	v_mov_b32_e32 v80, v0
	v_mov_b32_e32 v81, v0
	v_mov_b32_e32 v82, v0
	v_mov_b32_e32 v83, v0
	v_mov_b32_e32 v84, v0
	v_mov_b32_e32 v85, v0
	v_mov_b32_e32 v86, v0
	v_mov_b32_e32 v87, v0
	v_mov_b32_e32 v88, v0
	v_mov_b32_e32 v89, v0
	v_mov_b32_e32 v90, v0
	v_mov_b32_e32 v91, v0
	v_mov_b32_e32 v92, v0
	v_mov_b32_e32 v93, v0
	v_mov_b32_e32 v94, v0
	v_mov_b32_e32 v95, v0
	v_mov_b32_e32 v96, v0
	v_mov_b32_e32 v97, v0
	v_mov_b32_e32 v98, v0
	v_mov_b32_e32 v99, v0
	v_mov_b32_e32 v100, v0
	v_mov_b32_e32 v101, v0
	v_mov_b32_e32 v102, v0
	v_mov_b32_e32 v103, v0
	v_mov_b32_e32 v104, v0
	v_mov_b32_e32 v105, v0
	v_mov_b32_e32 v106, v0
	v_mov_b32_e32 v107, v0
	v_mov_b32_e32 v108, v0
	v_mov_b32_e32 v109, v0
	v_mov_b32_e32 v110, v0
	v_mov_b32_e32 v111, v0
	v_mov_b32_e32 v112, v0
	v_mov_b32_e32 v113, v0
	v_mov_b32_e32 v114, v0
	v_mov_b32_e32 v115, v0
	v_mov_b32_e32 v116, v0
	v_mov_b32_e32 v117, v0
	v_mov_b32_e32 v118, v0
	v_mov_b32_e32 v119, v0
	v_mov_b32_e32 v120, v0
	v_mov_b32_e32 v121, v0
	v_mov_b32_e32 v122, v0
	v_mov_b32_e32 v123, v0
	v_mov_b32_e32 v124, v0
	v_mov_b32_e32 v125, v0
	v_mov_b32_e32 v126, v0
	v_mov_b32_e32 v127, v0
	s_branch .LBB0_327

.LBB0_334:
	s_or_b64 exec, exec, s[20:21]
	v_lshl_add_u32 v140, s22, 7, v128
	v_ashrrev_i32_e32 v141, 31, v140
	v_mad_i64_i32 v[138:139], s[20:21], v140, s38, 0
	v_mad_i64_i32 v[142:143], s[20:21], v140, s38, v[130:131]
	v_lshlrev_b64 v[140:141], 11, v[140:141]
	s_xor_b64 s[18:19], s[18:19], -1
	v_lshl_add_u64 v[144:145], v[132:133], 0, v[140:141]
	s_mov_b32 s20, 0
	global_load_dwordx4 v[206:209], v[142:143], off offset:-8
	v_lshl_add_u64 v[142:143], v[142:143], 0, s[14:15]
	global_load_dwordx4 v[210:213], v[142:143], off offset:-8
	v_lshl_add_u64 v[142:143], v[142:143], 0, s[14:15]
	global_load_dwordx4 v[214:217], v[142:143], off offset:-8
	v_lshl_add_u64 v[142:143], v[142:143], 0, s[14:15]
	global_load_dwordx4 v[218:221], v[142:143], off offset:-8
	v_lshl_add_u64 v[142:143], v[142:143], 0, s[14:15]
	v_mov_b32_e32 v142, v144
	v_mov_b32_e32 v143, v145
	global_load_dwordx4 v[222:225], v[142:143], off offset:-8
	v_lshl_add_u64 v[142:143], v[142:143], 0, s[16:17]
	global_load_dwordx4 v[226:229], v[142:143], off offset:-8
	v_lshl_add_u64 v[142:143], v[142:143], 0, s[16:17]
	global_load_dwordx4 v[246:249], v[142:143], off offset:-8
	v_lshl_add_u64 v[142:143], v[142:143], 0, s[16:17]
	global_load_dwordx4 v[250:253], v[142:143], off offset:-8
	s_waitcnt lgkmcnt(0)
	s_barrier
.LBB0_335:
	v_add_u32_e32 v176, s20, v175
	ds_read_b128 v[194:197], v176
	ds_read_b128 v[198:201], v176 offset:16
	s_add_i32 s20, s20, 0x8200
	s_cmp_lg_u32 s20, 0x20800
	s_waitcnt vmcnt(7)
	v_lshlrev_b32_e32 v176, 16, v206
	v_and_b32_e32 v177, 0xffff0000, v206
	v_lshlrev_b32_e32 v180, 16, v207
	v_and_b32_e32 v181, 0xffff0000, v207
	v_lshlrev_b32_e32 v186, 16, v208
	v_and_b32_e32 v187, 0xffff0000, v208
	v_lshlrev_b32_e32 v188, 16, v209
	v_and_b32_e32 v189, 0xffff0000, v209
	s_waitcnt vmcnt(3)
	v_lshlrev_b32_e32 v202, 16, v222
	v_and_b32_e32 v203, 0xffff0000, v222
	v_lshlrev_b32_e32 v190, 16, v223
	v_and_b32_e32 v191, 0xffff0000, v223
	v_lshlrev_b32_e32 v204, 16, v224
	v_and_b32_e32 v205, 0xffff0000, v224
	v_lshlrev_b32_e32 v192, 16, v225
	v_and_b32_e32 v193, 0xffff0000, v225
	s_waitcnt lgkmcnt(1)
	v_pk_fma_f32 v[176:177], v[194:195], v[176:177], v[202:203]
	v_pk_fma_f32 v[180:181], v[196:197], v[180:181], v[190:191]
	s_waitcnt lgkmcnt(0)
	v_pk_fma_f32 v[190:191], v[198:199], v[186:187], v[204:205]
	v_pk_fma_f32 v[192:193], v[200:201], v[188:189], v[192:193]
	v_cvt_pk_bf16_f32 v186, v176, v177
	v_cvt_pk_bf16_f32 v187, v180, v181
	v_cvt_pk_bf16_f32 v188, v190, v191
	v_cvt_pk_bf16_f32 v189, v192, v193
	global_store_dwordx4 v[144:145], v[186:189], off offset:-8
	v_lshl_add_u64 v[144:145], v[144:145], 0, s[16:17]
	v_add_u32_e32 v176, s20, v175
	ds_read_b128 v[194:197], v176
	ds_read_b128 v[198:201], v176 offset:16
	s_add_i32 s20, s20, 0x8200
	s_cmp_lg_u32 s20, 0x20800
	s_waitcnt vmcnt(7)
	v_lshlrev_b32_e32 v176, 16, v210
	v_and_b32_e32 v177, 0xffff0000, v210
	v_lshlrev_b32_e32 v180, 16, v211
	v_and_b32_e32 v181, 0xffff0000, v211
	v_lshlrev_b32_e32 v186, 16, v212
	v_and_b32_e32 v187, 0xffff0000, v212
	v_lshlrev_b32_e32 v188, 16, v213
	v_and_b32_e32 v189, 0xffff0000, v213
	s_waitcnt vmcnt(3)
	v_lshlrev_b32_e32 v202, 16, v226
	v_and_b32_e32 v203, 0xffff0000, v226
	v_lshlrev_b32_e32 v190, 16, v227
	v_and_b32_e32 v191, 0xffff0000, v227
	v_lshlrev_b32_e32 v204, 16, v228
	v_and_b32_e32 v205, 0xffff0000, v228
	v_lshlrev_b32_e32 v192, 16, v229
	v_and_b32_e32 v193, 0xffff0000, v229
	s_waitcnt lgkmcnt(1)
	v_pk_fma_f32 v[176:177], v[194:195], v[176:177], v[202:203]
	v_pk_fma_f32 v[180:181], v[196:197], v[180:181], v[190:191]
	s_waitcnt lgkmcnt(0)
	v_pk_fma_f32 v[190:191], v[198:199], v[186:187], v[204:205]
	v_pk_fma_f32 v[192:193], v[200:201], v[188:189], v[192:193]
	v_cvt_pk_bf16_f32 v186, v176, v177
	v_cvt_pk_bf16_f32 v187, v180, v181
	v_cvt_pk_bf16_f32 v188, v190, v191
	v_cvt_pk_bf16_f32 v189, v192, v193
	global_store_dwordx4 v[144:145], v[186:189], off offset:-8
	v_lshl_add_u64 v[144:145], v[144:145], 0, s[16:17]
	v_add_u32_e32 v176, s20, v175
	ds_read_b128 v[194:197], v176
	ds_read_b128 v[198:201], v176 offset:16
	s_add_i32 s20, s20, 0x8200
	s_cmp_lg_u32 s20, 0x20800
	s_waitcnt vmcnt(7)
	v_lshlrev_b32_e32 v176, 16, v214
	v_and_b32_e32 v177, 0xffff0000, v214
	v_lshlrev_b32_e32 v180, 16, v215
	v_and_b32_e32 v181, 0xffff0000, v215
	v_lshlrev_b32_e32 v186, 16, v216
	v_and_b32_e32 v187, 0xffff0000, v216
	v_lshlrev_b32_e32 v188, 16, v217
	v_and_b32_e32 v189, 0xffff0000, v217
	s_waitcnt vmcnt(3)
	v_lshlrev_b32_e32 v202, 16, v246
	v_and_b32_e32 v203, 0xffff0000, v246
	v_lshlrev_b32_e32 v190, 16, v247
	v_and_b32_e32 v191, 0xffff0000, v247
	v_lshlrev_b32_e32 v204, 16, v248
	v_and_b32_e32 v205, 0xffff0000, v248
	v_lshlrev_b32_e32 v192, 16, v249
	v_and_b32_e32 v193, 0xffff0000, v249
	s_waitcnt lgkmcnt(1)
	v_pk_fma_f32 v[176:177], v[194:195], v[176:177], v[202:203]
	v_pk_fma_f32 v[180:181], v[196:197], v[180:181], v[190:191]
	s_waitcnt lgkmcnt(0)
	v_pk_fma_f32 v[190:191], v[198:199], v[186:187], v[204:205]
	v_pk_fma_f32 v[192:193], v[200:201], v[188:189], v[192:193]
	v_cvt_pk_bf16_f32 v186, v176, v177
	v_cvt_pk_bf16_f32 v187, v180, v181
	v_cvt_pk_bf16_f32 v188, v190, v191
	v_cvt_pk_bf16_f32 v189, v192, v193
	global_store_dwordx4 v[144:145], v[186:189], off offset:-8
	v_lshl_add_u64 v[144:145], v[144:145], 0, s[16:17]
	v_add_u32_e32 v176, s20, v175
	ds_read_b128 v[194:197], v176
	ds_read_b128 v[198:201], v176 offset:16
	s_add_i32 s20, s20, 0x8200
	s_cmp_lg_u32 s20, 0x20800
	s_waitcnt vmcnt(7)
	v_lshlrev_b32_e32 v176, 16, v218
	v_and_b32_e32 v177, 0xffff0000, v218
	v_lshlrev_b32_e32 v180, 16, v219
	v_and_b32_e32 v181, 0xffff0000, v219
	v_lshlrev_b32_e32 v186, 16, v220
	v_and_b32_e32 v187, 0xffff0000, v220
	v_lshlrev_b32_e32 v188, 16, v221
	v_and_b32_e32 v189, 0xffff0000, v221
	s_waitcnt vmcnt(3)
	v_lshlrev_b32_e32 v202, 16, v250
	v_and_b32_e32 v203, 0xffff0000, v250
	v_lshlrev_b32_e32 v190, 16, v251
	v_and_b32_e32 v191, 0xffff0000, v251
	v_lshlrev_b32_e32 v204, 16, v252
	v_and_b32_e32 v205, 0xffff0000, v252
	v_lshlrev_b32_e32 v192, 16, v253
	v_and_b32_e32 v193, 0xffff0000, v253
	s_waitcnt lgkmcnt(1)
	v_pk_fma_f32 v[176:177], v[194:195], v[176:177], v[202:203]
	v_pk_fma_f32 v[180:181], v[196:197], v[180:181], v[190:191]
	s_waitcnt lgkmcnt(0)
	v_pk_fma_f32 v[190:191], v[198:199], v[186:187], v[204:205]
	v_pk_fma_f32 v[192:193], v[200:201], v[188:189], v[192:193]
	v_cvt_pk_bf16_f32 v186, v176, v177
	v_cvt_pk_bf16_f32 v187, v180, v181
	v_cvt_pk_bf16_f32 v188, v190, v191
	v_cvt_pk_bf16_f32 v189, v192, v193
	global_store_dwordx4 v[144:145], v[186:189], off offset:-8
	v_lshl_add_u64 v[144:145], v[144:145], 0, s[16:17]
	v_lshl_add_u64 v[138:139], v[134:135], 0, v[138:139]
	v_lshl_add_u64 v[140:141], v[136:137], 0, v[140:141]
	s_movk_i32 s20, 0x200
	global_load_dwordx4 v[206:209], v[138:139], off offset:-8
	v_lshl_add_u64 v[138:139], v[138:139], 0, s[14:15]
	global_load_dwordx4 v[210:213], v[138:139], off offset:-8
	v_lshl_add_u64 v[138:139], v[138:139], 0, s[14:15]
	global_load_dwordx4 v[214:217], v[138:139], off offset:-8
	v_lshl_add_u64 v[138:139], v[138:139], 0, s[14:15]
	global_load_dwordx4 v[218:221], v[138:139], off offset:-8
	v_lshl_add_u64 v[138:139], v[138:139], 0, s[14:15]
	v_mov_b32_e32 v138, v140
	v_mov_b32_e32 v139, v141
	global_load_dwordx4 v[222:225], v[138:139], off offset:-8
	v_lshl_add_u64 v[138:139], v[138:139], 0, s[16:17]
	global_load_dwordx4 v[226:229], v[138:139], off offset:-8
	v_lshl_add_u64 v[138:139], v[138:139], 0, s[16:17]
	global_load_dwordx4 v[246:249], v[138:139], off offset:-8
	v_lshl_add_u64 v[138:139], v[138:139], 0, s[16:17]
	global_load_dwordx4 v[250:253], v[138:139], off offset:-8
.LBB0_337:
	v_add_u32_e32 v176, s20, v175
	ds_read_b128 v[190:193], v176
	ds_read_b128 v[194:197], v176 offset:16
	s_add_i32 s20, s20, 0x8200
	s_cmp_lg_u32 s20, 0x20a00
	s_waitcnt vmcnt(7)
	v_lshlrev_b32_e32 v176, 16, v206
	v_and_b32_e32 v177, 0xffff0000, v206
	v_lshlrev_b32_e32 v142, 16, v207
	v_and_b32_e32 v143, 0xffff0000, v207
	v_lshlrev_b32_e32 v180, 16, v208
	v_and_b32_e32 v181, 0xffff0000, v208
	v_lshlrev_b32_e32 v144, 16, v209
	v_and_b32_e32 v145, 0xffff0000, v209
	s_waitcnt vmcnt(3)
	v_lshlrev_b32_e32 v198, 16, v222
	v_and_b32_e32 v199, 0xffff0000, v222
	v_lshlrev_b32_e32 v186, 16, v223
	v_and_b32_e32 v187, 0xffff0000, v223
	v_lshlrev_b32_e32 v200, 16, v224
	v_and_b32_e32 v201, 0xffff0000, v224
	v_lshlrev_b32_e32 v188, 16, v225
	v_and_b32_e32 v189, 0xffff0000, v225
	s_waitcnt lgkmcnt(1)
	v_pk_fma_f32 v[176:177], v[190:191], v[176:177], v[198:199]
	v_pk_fma_f32 v[186:187], v[192:193], v[142:143], v[186:187]
	s_waitcnt lgkmcnt(0)
	v_pk_fma_f32 v[180:181], v[194:195], v[180:181], v[200:201]
	v_pk_fma_f32 v[188:189], v[196:197], v[144:145], v[188:189]
	v_cvt_pk_bf16_f32 v142, v176, v177
	v_cvt_pk_bf16_f32 v143, v186, v187
	v_cvt_pk_bf16_f32 v144, v180, v181
	v_cvt_pk_bf16_f32 v145, v188, v189
	global_store_dwordx4 v[140:141], v[142:145], off offset:-8
	v_lshl_add_u64 v[140:141], v[140:141], 0, s[16:17]
	v_add_u32_e32 v176, s20, v175
	ds_read_b128 v[190:193], v176
	ds_read_b128 v[194:197], v176 offset:16
	s_add_i32 s20, s20, 0x8200
	s_cmp_lg_u32 s20, 0x20a00
	s_waitcnt vmcnt(7)
	v_lshlrev_b32_e32 v176, 16, v210
	v_and_b32_e32 v177, 0xffff0000, v210
	v_lshlrev_b32_e32 v142, 16, v211
	v_and_b32_e32 v143, 0xffff0000, v211
	v_lshlrev_b32_e32 v180, 16, v212
	v_and_b32_e32 v181, 0xffff0000, v212
	v_lshlrev_b32_e32 v144, 16, v213
	v_and_b32_e32 v145, 0xffff0000, v213
	s_waitcnt vmcnt(3)
	v_lshlrev_b32_e32 v198, 16, v226
	v_and_b32_e32 v199, 0xffff0000, v226
	v_lshlrev_b32_e32 v186, 16, v227
	v_and_b32_e32 v187, 0xffff0000, v227
	v_lshlrev_b32_e32 v200, 16, v228
	v_and_b32_e32 v201, 0xffff0000, v228
	v_lshlrev_b32_e32 v188, 16, v229
	v_and_b32_e32 v189, 0xffff0000, v229
	s_waitcnt lgkmcnt(1)
	v_pk_fma_f32 v[176:177], v[190:191], v[176:177], v[198:199]
	v_pk_fma_f32 v[186:187], v[192:193], v[142:143], v[186:187]
	s_waitcnt lgkmcnt(0)
	v_pk_fma_f32 v[180:181], v[194:195], v[180:181], v[200:201]
	v_pk_fma_f32 v[188:189], v[196:197], v[144:145], v[188:189]
	v_cvt_pk_bf16_f32 v142, v176, v177
	v_cvt_pk_bf16_f32 v143, v186, v187
	v_cvt_pk_bf16_f32 v144, v180, v181
	v_cvt_pk_bf16_f32 v145, v188, v189
	global_store_dwordx4 v[140:141], v[142:145], off offset:-8
	v_lshl_add_u64 v[140:141], v[140:141], 0, s[16:17]
	v_add_u32_e32 v176, s20, v175
	ds_read_b128 v[190:193], v176
	ds_read_b128 v[194:197], v176 offset:16
	s_add_i32 s20, s20, 0x8200
	s_cmp_lg_u32 s20, 0x20a00
	s_waitcnt vmcnt(7)
	v_lshlrev_b32_e32 v176, 16, v214
	v_and_b32_e32 v177, 0xffff0000, v214
	v_lshlrev_b32_e32 v142, 16, v215
	v_and_b32_e32 v143, 0xffff0000, v215
	v_lshlrev_b32_e32 v180, 16, v216
	v_and_b32_e32 v181, 0xffff0000, v216
	v_lshlrev_b32_e32 v144, 16, v217
	v_and_b32_e32 v145, 0xffff0000, v217
	s_waitcnt vmcnt(3)
	v_lshlrev_b32_e32 v198, 16, v246
	v_and_b32_e32 v199, 0xffff0000, v246
	v_lshlrev_b32_e32 v186, 16, v247
	v_and_b32_e32 v187, 0xffff0000, v247
	v_lshlrev_b32_e32 v200, 16, v248
	v_and_b32_e32 v201, 0xffff0000, v248
	v_lshlrev_b32_e32 v188, 16, v249
	v_and_b32_e32 v189, 0xffff0000, v249
	s_waitcnt lgkmcnt(1)
	v_pk_fma_f32 v[176:177], v[190:191], v[176:177], v[198:199]
	v_pk_fma_f32 v[186:187], v[192:193], v[142:143], v[186:187]
	s_waitcnt lgkmcnt(0)
	v_pk_fma_f32 v[180:181], v[194:195], v[180:181], v[200:201]
	v_pk_fma_f32 v[188:189], v[196:197], v[144:145], v[188:189]
	v_cvt_pk_bf16_f32 v142, v176, v177
	v_cvt_pk_bf16_f32 v143, v186, v187
	v_cvt_pk_bf16_f32 v144, v180, v181
	v_cvt_pk_bf16_f32 v145, v188, v189
	global_store_dwordx4 v[140:141], v[142:145], off offset:-8
	v_lshl_add_u64 v[140:141], v[140:141], 0, s[16:17]
	v_add_u32_e32 v176, s20, v175
	ds_read_b128 v[190:193], v176
	ds_read_b128 v[194:197], v176 offset:16
	s_add_i32 s20, s20, 0x8200
	s_cmp_lg_u32 s20, 0x20a00
	s_waitcnt vmcnt(7)
	v_lshlrev_b32_e32 v176, 16, v218
	v_and_b32_e32 v177, 0xffff0000, v218
	v_lshlrev_b32_e32 v142, 16, v219
	v_and_b32_e32 v143, 0xffff0000, v219
	v_lshlrev_b32_e32 v180, 16, v220
	v_and_b32_e32 v181, 0xffff0000, v220
	v_lshlrev_b32_e32 v144, 16, v221
	v_and_b32_e32 v145, 0xffff0000, v221
	s_waitcnt vmcnt(3)
	v_lshlrev_b32_e32 v198, 16, v250
	v_and_b32_e32 v199, 0xffff0000, v250
	v_lshlrev_b32_e32 v186, 16, v251
	v_and_b32_e32 v187, 0xffff0000, v251
	v_lshlrev_b32_e32 v200, 16, v252
	v_and_b32_e32 v201, 0xffff0000, v252
	v_lshlrev_b32_e32 v188, 16, v253
	v_and_b32_e32 v189, 0xffff0000, v253
	s_waitcnt lgkmcnt(1)
	v_pk_fma_f32 v[176:177], v[190:191], v[176:177], v[198:199]
	v_pk_fma_f32 v[186:187], v[192:193], v[142:143], v[186:187]
	s_waitcnt lgkmcnt(0)
	v_pk_fma_f32 v[180:181], v[194:195], v[180:181], v[200:201]
	v_pk_fma_f32 v[188:189], v[196:197], v[144:145], v[188:189]
	v_cvt_pk_bf16_f32 v142, v176, v177
	v_cvt_pk_bf16_f32 v143, v186, v187
	v_cvt_pk_bf16_f32 v144, v180, v181
	v_cvt_pk_bf16_f32 v145, v188, v189
	global_store_dwordx4 v[140:141], v[142:145], off offset:-8
	v_lshl_add_u64 v[140:141], v[140:141], 0, s[16:17]
	s_mov_b32 s22, 1
	s_andn2_b64 vcc, exec, s[18:19]
	s_mov_b64 s[18:19], 0
	s_cbranch_vccnz .LBB0_332
	s_add_i32 s40, s40, s90
	s_add_i32 s35, s35, s36
	s_add_i32 s39, s39, s84
	s_cmpk_lt_i32 s40, 0x100
	s_cbranch_scc1 .LBB0_311

.LBB0_905:
	s_or_b64 exec, exec, s[22:23]
	v_lshl_add_u32 v140, s33, 7, v175
	v_ashrrev_i32_e32 v141, 31, v140
	v_mad_i64_i32 v[138:139], s[22:23], v140, s37, 0
	v_mad_i64_i32 v[142:143], s[22:23], v140, s37, v[130:131]
	v_lshlrev_b64 v[140:141], 11, v[140:141]
	s_xor_b64 s[20:21], s[20:21], -1
	v_lshl_add_u64 v[144:145], v[132:133], 0, v[140:141]
	s_mov_b32 s22, 0
	global_load_dwordx4 v[198:201], v[142:143], off offset:-8
	v_lshl_add_u64 v[142:143], v[142:143], 0, s[12:13]
	global_load_dwordx4 v[202:205], v[142:143], off offset:-8
	v_lshl_add_u64 v[142:143], v[142:143], 0, s[12:13]
	global_load_dwordx4 v[206:209], v[142:143], off offset:-8
	v_lshl_add_u64 v[142:143], v[142:143], 0, s[12:13]
	global_load_dwordx4 v[210:213], v[142:143], off offset:-8
	v_lshl_add_u64 v[142:143], v[142:143], 0, s[12:13]
	s_waitcnt lgkmcnt(0)
	s_barrier
.LBB0_906:
	v_add_u32_e32 v176, s22, v174
	ds_read_b128 v[186:189], v176
	ds_read_b128 v[190:193], v176 offset:16
	s_add_i32 s22, s22, 0x8200
	s_cmp_lg_u32 s22, 0x20800
	s_waitcnt vmcnt(3)
	v_lshlrev_b32_e32 v176, 16, v198
	v_and_b32_e32 v177, 0xffff0000, v198
	v_lshlrev_b32_e32 v180, 16, v199
	v_and_b32_e32 v181, 0xffff0000, v199
	v_lshlrev_b32_e32 v182, 16, v200
	v_and_b32_e32 v183, 0xffff0000, v200
	v_lshlrev_b32_e32 v184, 16, v201
	v_and_b32_e32 v185, 0xffff0000, v201
	s_waitcnt lgkmcnt(1)
	v_pk_mul_f32 v[176:177], v[186:187], v[176:177]
	v_pk_mul_f32 v[180:181], v[188:189], v[180:181]
	s_waitcnt lgkmcnt(0)
	v_pk_mul_f32 v[186:187], v[190:191], v[182:183]
	v_pk_mul_f32 v[188:189], v[192:193], v[184:185]
	v_cvt_pk_bf16_f32 v182, v176, v177
	v_cvt_pk_bf16_f32 v183, v180, v181
	v_cvt_pk_bf16_f32 v184, v186, v187
	v_cvt_pk_bf16_f32 v185, v188, v189
	global_store_dwordx4 v[144:145], v[182:185], off offset:-8
	v_lshl_add_u64 v[144:145], v[144:145], 0, s[14:15]
	v_add_u32_e32 v176, s22, v174
	ds_read_b128 v[186:189], v176
	ds_read_b128 v[190:193], v176 offset:16
	s_add_i32 s22, s22, 0x8200
	s_cmp_lg_u32 s22, 0x20800
	s_waitcnt vmcnt(3)
	v_lshlrev_b32_e32 v176, 16, v202
	v_and_b32_e32 v177, 0xffff0000, v202
	v_lshlrev_b32_e32 v180, 16, v203
	v_and_b32_e32 v181, 0xffff0000, v203
	v_lshlrev_b32_e32 v182, 16, v204
	v_and_b32_e32 v183, 0xffff0000, v204
	v_lshlrev_b32_e32 v184, 16, v205
	v_and_b32_e32 v185, 0xffff0000, v205
	s_waitcnt lgkmcnt(1)
	v_pk_mul_f32 v[176:177], v[186:187], v[176:177]
	v_pk_mul_f32 v[180:181], v[188:189], v[180:181]
	s_waitcnt lgkmcnt(0)
	v_pk_mul_f32 v[186:187], v[190:191], v[182:183]
	v_pk_mul_f32 v[188:189], v[192:193], v[184:185]
	v_cvt_pk_bf16_f32 v182, v176, v177
	v_cvt_pk_bf16_f32 v183, v180, v181
	v_cvt_pk_bf16_f32 v184, v186, v187
	v_cvt_pk_bf16_f32 v185, v188, v189
	global_store_dwordx4 v[144:145], v[182:185], off offset:-8
	v_lshl_add_u64 v[144:145], v[144:145], 0, s[14:15]
	v_add_u32_e32 v176, s22, v174
	ds_read_b128 v[186:189], v176
	ds_read_b128 v[190:193], v176 offset:16
	s_add_i32 s22, s22, 0x8200
	s_cmp_lg_u32 s22, 0x20800
	s_waitcnt vmcnt(3)
	v_lshlrev_b32_e32 v176, 16, v206
	v_and_b32_e32 v177, 0xffff0000, v206
	v_lshlrev_b32_e32 v180, 16, v207
	v_and_b32_e32 v181, 0xffff0000, v207
	v_lshlrev_b32_e32 v182, 16, v208
	v_and_b32_e32 v183, 0xffff0000, v208
	v_lshlrev_b32_e32 v184, 16, v209
	v_and_b32_e32 v185, 0xffff0000, v209
	s_waitcnt lgkmcnt(1)
	v_pk_mul_f32 v[176:177], v[186:187], v[176:177]
	v_pk_mul_f32 v[180:181], v[188:189], v[180:181]
	s_waitcnt lgkmcnt(0)
	v_pk_mul_f32 v[186:187], v[190:191], v[182:183]
	v_pk_mul_f32 v[188:189], v[192:193], v[184:185]
	v_cvt_pk_bf16_f32 v182, v176, v177
	v_cvt_pk_bf16_f32 v183, v180, v181
	v_cvt_pk_bf16_f32 v184, v186, v187
	v_cvt_pk_bf16_f32 v185, v188, v189
	global_store_dwordx4 v[144:145], v[182:185], off offset:-8
	v_lshl_add_u64 v[144:145], v[144:145], 0, s[14:15]
	v_add_u32_e32 v176, s22, v174
	ds_read_b128 v[186:189], v176
	ds_read_b128 v[190:193], v176 offset:16
	s_add_i32 s22, s22, 0x8200
	s_cmp_lg_u32 s22, 0x20800
	s_waitcnt vmcnt(3)
	v_lshlrev_b32_e32 v176, 16, v210
	v_and_b32_e32 v177, 0xffff0000, v210
	v_lshlrev_b32_e32 v180, 16, v211
	v_and_b32_e32 v181, 0xffff0000, v211
	v_lshlrev_b32_e32 v182, 16, v212
	v_and_b32_e32 v183, 0xffff0000, v212
	v_lshlrev_b32_e32 v184, 16, v213
	v_and_b32_e32 v185, 0xffff0000, v213
	s_waitcnt lgkmcnt(1)
	v_pk_mul_f32 v[176:177], v[186:187], v[176:177]
	v_pk_mul_f32 v[180:181], v[188:189], v[180:181]
	s_waitcnt lgkmcnt(0)
	v_pk_mul_f32 v[186:187], v[190:191], v[182:183]
	v_pk_mul_f32 v[188:189], v[192:193], v[184:185]
	v_cvt_pk_bf16_f32 v182, v176, v177
	v_cvt_pk_bf16_f32 v183, v180, v181
	v_cvt_pk_bf16_f32 v184, v186, v187
	v_cvt_pk_bf16_f32 v185, v188, v189
	global_store_dwordx4 v[144:145], v[182:185], off offset:-8
	v_lshl_add_u64 v[144:145], v[144:145], 0, s[14:15]
	v_lshl_add_u64 v[138:139], v[134:135], 0, v[138:139]
	v_lshl_add_u64 v[140:141], v[136:137], 0, v[140:141]
	s_movk_i32 s22, 0x200
	global_load_dwordx4 v[198:201], v[138:139], off offset:-8
	v_lshl_add_u64 v[138:139], v[138:139], 0, s[12:13]
	global_load_dwordx4 v[202:205], v[138:139], off offset:-8
	v_lshl_add_u64 v[138:139], v[138:139], 0, s[12:13]
	global_load_dwordx4 v[206:209], v[138:139], off offset:-8
	v_lshl_add_u64 v[138:139], v[138:139], 0, s[12:13]
	global_load_dwordx4 v[210:213], v[138:139], off offset:-8
	v_lshl_add_u64 v[138:139], v[138:139], 0, s[12:13]
.LBB0_908:
	v_add_u32_e32 v176, s22, v174
	ds_read_b128 v[182:185], v176
	ds_read_b128 v[186:189], v176 offset:16
	s_add_i32 s22, s22, 0x8200
	s_cmp_lg_u32 s22, 0x20a00
	s_waitcnt vmcnt(3)
	v_lshlrev_b32_e32 v176, 16, v198
	v_and_b32_e32 v177, 0xffff0000, v198
	v_lshlrev_b32_e32 v142, 16, v199
	v_and_b32_e32 v143, 0xffff0000, v199
	v_lshlrev_b32_e32 v180, 16, v200
	v_and_b32_e32 v181, 0xffff0000, v200
	v_lshlrev_b32_e32 v144, 16, v201
	v_and_b32_e32 v145, 0xffff0000, v201
	s_waitcnt lgkmcnt(1)
	v_pk_mul_f32 v[176:177], v[182:183], v[176:177]
	v_pk_mul_f32 v[182:183], v[184:185], v[142:143]
	s_waitcnt lgkmcnt(0)
	v_pk_mul_f32 v[180:181], v[186:187], v[180:181]
	v_pk_mul_f32 v[184:185], v[188:189], v[144:145]
	v_cvt_pk_bf16_f32 v142, v176, v177
	v_cvt_pk_bf16_f32 v143, v182, v183
	v_cvt_pk_bf16_f32 v144, v180, v181
	v_cvt_pk_bf16_f32 v145, v184, v185
	global_store_dwordx4 v[140:141], v[142:145], off offset:-8
	v_lshl_add_u64 v[140:141], v[140:141], 0, s[14:15]
	v_add_u32_e32 v176, s22, v174
	ds_read_b128 v[182:185], v176
	ds_read_b128 v[186:189], v176 offset:16
	s_add_i32 s22, s22, 0x8200
	s_cmp_lg_u32 s22, 0x20a00
	s_waitcnt vmcnt(3)
	v_lshlrev_b32_e32 v176, 16, v202
	v_and_b32_e32 v177, 0xffff0000, v202
	v_lshlrev_b32_e32 v142, 16, v203
	v_and_b32_e32 v143, 0xffff0000, v203
	v_lshlrev_b32_e32 v180, 16, v204
	v_and_b32_e32 v181, 0xffff0000, v204
	v_lshlrev_b32_e32 v144, 16, v205
	v_and_b32_e32 v145, 0xffff0000, v205
	s_waitcnt lgkmcnt(1)
	v_pk_mul_f32 v[176:177], v[182:183], v[176:177]
	v_pk_mul_f32 v[182:183], v[184:185], v[142:143]
	s_waitcnt lgkmcnt(0)
	v_pk_mul_f32 v[180:181], v[186:187], v[180:181]
	v_pk_mul_f32 v[184:185], v[188:189], v[144:145]
	v_cvt_pk_bf16_f32 v142, v176, v177
	v_cvt_pk_bf16_f32 v143, v182, v183
	v_cvt_pk_bf16_f32 v144, v180, v181
	v_cvt_pk_bf16_f32 v145, v184, v185
	global_store_dwordx4 v[140:141], v[142:145], off offset:-8
	v_lshl_add_u64 v[140:141], v[140:141], 0, s[14:15]
	v_add_u32_e32 v176, s22, v174
	ds_read_b128 v[182:185], v176
	ds_read_b128 v[186:189], v176 offset:16
	s_add_i32 s22, s22, 0x8200
	s_cmp_lg_u32 s22, 0x20a00
	s_waitcnt vmcnt(3)
	v_lshlrev_b32_e32 v176, 16, v206
	v_and_b32_e32 v177, 0xffff0000, v206
	v_lshlrev_b32_e32 v142, 16, v207
	v_and_b32_e32 v143, 0xffff0000, v207
	v_lshlrev_b32_e32 v180, 16, v208
	v_and_b32_e32 v181, 0xffff0000, v208
	v_lshlrev_b32_e32 v144, 16, v209
	v_and_b32_e32 v145, 0xffff0000, v209
	s_waitcnt lgkmcnt(1)
	v_pk_mul_f32 v[176:177], v[182:183], v[176:177]
	v_pk_mul_f32 v[182:183], v[184:185], v[142:143]
	s_waitcnt lgkmcnt(0)
	v_pk_mul_f32 v[180:181], v[186:187], v[180:181]
	v_pk_mul_f32 v[184:185], v[188:189], v[144:145]
	v_cvt_pk_bf16_f32 v142, v176, v177
	v_cvt_pk_bf16_f32 v143, v182, v183
	v_cvt_pk_bf16_f32 v144, v180, v181
	v_cvt_pk_bf16_f32 v145, v184, v185
	global_store_dwordx4 v[140:141], v[142:145], off offset:-8
	v_lshl_add_u64 v[140:141], v[140:141], 0, s[14:15]
	v_add_u32_e32 v176, s22, v174
	ds_read_b128 v[182:185], v176
	ds_read_b128 v[186:189], v176 offset:16
	s_add_i32 s22, s22, 0x8200
	s_cmp_lg_u32 s22, 0x20a00
	s_waitcnt vmcnt(3)
	v_lshlrev_b32_e32 v176, 16, v210
	v_and_b32_e32 v177, 0xffff0000, v210
	v_lshlrev_b32_e32 v142, 16, v211
	v_and_b32_e32 v143, 0xffff0000, v211
	v_lshlrev_b32_e32 v180, 16, v212
	v_and_b32_e32 v181, 0xffff0000, v212
	v_lshlrev_b32_e32 v144, 16, v213
	v_and_b32_e32 v145, 0xffff0000, v213
	s_waitcnt lgkmcnt(1)
	v_pk_mul_f32 v[176:177], v[182:183], v[176:177]
	v_pk_mul_f32 v[182:183], v[184:185], v[142:143]
	s_waitcnt lgkmcnt(0)
	v_pk_mul_f32 v[180:181], v[186:187], v[180:181]
	v_pk_mul_f32 v[184:185], v[188:189], v[144:145]
	v_cvt_pk_bf16_f32 v142, v176, v177
	v_cvt_pk_bf16_f32 v143, v182, v183
	v_cvt_pk_bf16_f32 v144, v180, v181
	v_cvt_pk_bf16_f32 v145, v184, v185
	global_store_dwordx4 v[140:141], v[142:145], off offset:-8
	v_lshl_add_u64 v[140:141], v[140:141], 0, s[14:15]
	s_mov_b32 s33, 1
	s_andn2_b64 vcc, exec, s[20:21]
	s_mov_b64 s[20:21], 0
	s_cbranch_vccnz .LBB0_903
	s_lshl_b32 s20, s42, 1
	s_add_u32 s22, s30, s20
	s_addc_u32 s23, s31, 0
	s_lshl_b64 s[18:19], s[18:19], 1
	s_add_u32 s33, s28, s18
	v_readfirstlane_b32 s18, v146
	s_addc_u32 s42, s29, s19
	s_ashr_i32 s43, s18, 6
	s_lshl_b32 s18, s43, 5
	s_ashr_i32 s19, s18, 31
	s_lshl_b64 s[20:21], s[18:19], 11
	s_add_u32 s20, s22, s20
	s_addc_u32 s21, s23, s21
	s_lshl_b64 s[18:19], s[18:19], 10
	s_add_u32 s18, s33, s18
	s_addc_u32 s19, s42, s19
	s_lshl_b32 s22, s43, 12
	s_add_i32 s23, s22, 0x8000
	s_add_u32 s42, s20, 0x4000
	s_barrier
	s_mov_b32 m0, s22
	global_load_lds_dwordx4 v147, s[20:21]
	s_addc_u32 s43, s21, 0
	s_or_b32 s33, s22, 0x400
	s_mov_b32 m0, s33
	global_load_lds_dwordx4 v148, s[42:43]
	s_add_u32 s42, s20, 0x8000
	s_addc_u32 s43, s21, 0
	s_or_b32 s33, s22, 0x800
	s_mov_b32 m0, s33
	global_load_lds_dwordx4 v147, s[42:43]
	s_add_u32 s42, s20, 0xc000
	s_addc_u32 s43, s21, 0
	s_or_b32 s33, s22, 0xc00
	s_mov_b32 m0, s33
	global_load_lds_dwordx4 v148, s[42:43]
	s_add_u32 s42, s18, 0x2000
	s_mov_b32 m0, s23
	global_load_lds_dwordx4 v149, s[18:19]
	s_addc_u32 s43, s19, 0
	s_add_i32 s23, s22, 0x8400
	s_mov_b32 m0, s23
	global_load_lds_dwordx4 v150, s[42:43]
	s_add_u32 s42, s18, 0x4000
	s_addc_u32 s43, s19, 0
	s_add_i32 s23, s22, 0x8800
	s_mov_b32 m0, s23
	global_load_lds_dwordx4 v149, s[42:43]
	s_add_u32 s42, s18, 0x6000
	s_addc_u32 s43, s19, 0
	s_add_i32 s23, s22, 0x8c00
	s_mov_b32 m0, s23
	global_load_lds_dwordx4 v150, s[42:43]
	s_add_u32 s23, s18, 0x6080
	s_addc_u32 s33, s19, 0
	s_add_u32 s42, s18, 0x4080
	s_addc_u32 s43, s19, 0
	s_add_u32 s44, s18, 0x2080
	s_addc_u32 s45, s19, 0
	s_add_u32 s46, s18, 0x80
	s_addc_u32 s47, s19, 0
	s_add_u32 s48, s20, 0xc080
	s_addc_u32 s49, s21, 0
	s_add_u32 s50, s20, 0x8080
	s_addc_u32 s51, s21, 0
	s_add_u32 s52, s20, 0x4080
	s_addc_u32 s53, s21, 0
	s_add_u32 s54, s20, 0x80
	v_mov_b32_e32 v0, 0
	s_addc_u32 s55, s21, 0
	s_mov_b32 s57, 0
	s_mov_b64 s[18:19], 0
	s_mov_b32 s56, 0
	v_mov_b32_e32 v1, v0
	v_mov_b32_e32 v2, v0
	v_mov_b32_e32 v3, v0
	v_mov_b32_e32 v4, v0
	v_mov_b32_e32 v5, v0
	v_mov_b32_e32 v6, v0
	v_mov_b32_e32 v7, v0
	v_mov_b32_e32 v8, v0
	v_mov_b32_e32 v9, v0
	v_mov_b32_e32 v10, v0
	v_mov_b32_e32 v11, v0
	v_mov_b32_e32 v12, v0
	v_mov_b32_e32 v13, v0
	v_mov_b32_e32 v14, v0
	v_mov_b32_e32 v15, v0
	v_mov_b32_e32 v16, v0
	v_mov_b32_e32 v17, v0
	v_mov_b32_e32 v18, v0
	v_mov_b32_e32 v19, v0
	v_mov_b32_e32 v20, v0
	v_mov_b32_e32 v21, v0
	v_mov_b32_e32 v22, v0
	v_mov_b32_e32 v23, v0
	v_mov_b32_e32 v24, v0
	v_mov_b32_e32 v25, v0
	v_mov_b32_e32 v26, v0
	v_mov_b32_e32 v27, v0
	v_mov_b32_e32 v28, v0
	v_mov_b32_e32 v29, v0
	v_mov_b32_e32 v30, v0
	v_mov_b32_e32 v31, v0
	v_mov_b32_e32 v32, v0
	v_mov_b32_e32 v33, v0
	v_mov_b32_e32 v34, v0
	v_mov_b32_e32 v35, v0
	v_mov_b32_e32 v36, v0
	v_mov_b32_e32 v37, v0
	v_mov_b32_e32 v38, v0
	v_mov_b32_e32 v39, v0
	v_mov_b32_e32 v40, v0
	v_mov_b32_e32 v41, v0
	v_mov_b32_e32 v42, v0
	v_mov_b32_e32 v43, v0
	v_mov_b32_e32 v44, v0
	v_mov_b32_e32 v45, v0
	v_mov_b32_e32 v46, v0
	v_mov_b32_e32 v47, v0
	v_mov_b32_e32 v48, v0
	v_mov_b32_e32 v49, v0
	v_mov_b32_e32 v50, v0
	v_mov_b32_e32 v51, v0
	v_mov_b32_e32 v52, v0
	v_mov_b32_e32 v53, v0
	v_mov_b32_e32 v54, v0
	v_mov_b32_e32 v55, v0
	v_mov_b32_e32 v56, v0
	v_mov_b32_e32 v57, v0
	v_mov_b32_e32 v58, v0
	v_mov_b32_e32 v59, v0
	v_mov_b32_e32 v60, v0
	v_mov_b32_e32 v61, v0
	v_mov_b32_e32 v62, v0
	v_mov_b32_e32 v63, v0
	v_mov_b32_e32 v64, v0
	v_mov_b32_e32 v65, v0
	v_mov_b32_e32 v66, v0
	v_mov_b32_e32 v67, v0
	v_mov_b32_e32 v68, v0
	v_mov_b32_e32 v69, v0
	v_mov_b32_e32 v70, v0
	v_mov_b32_e32 v71, v0
	v_mov_b32_e32 v72, v0
	v_mov_b32_e32 v73, v0
	v_mov_b32_e32 v74, v0
	v_mov_b32_e32 v75, v0
	v_mov_b32_e32 v76, v0
	v_mov_b32_e32 v77, v0
	v_mov_b32_e32 v78, v0
	v_mov_b32_e32 v79, v0
	v_mov_b32_e32 v80, v0
	v_mov_b32_e32 v81, v0
	v_mov_b32_e32 v82, v0
	v_mov_b32_e32 v83, v0
	v_mov_b32_e32 v84, v0
	v_mov_b32_e32 v85, v0
	v_mov_b32_e32 v86, v0
	v_mov_b32_e32 v87, v0
	v_mov_b32_e32 v88, v0
	v_mov_b32_e32 v89, v0
	v_mov_b32_e32 v90, v0
	v_mov_b32_e32 v91, v0
	v_mov_b32_e32 v92, v0
	v_mov_b32_e32 v93, v0
	v_mov_b32_e32 v94, v0
	v_mov_b32_e32 v95, v0
	v_mov_b32_e32 v96, v0
	v_mov_b32_e32 v97, v0
	v_mov_b32_e32 v98, v0
	v_mov_b32_e32 v99, v0
	v_mov_b32_e32 v100, v0
	v_mov_b32_e32 v101, v0
	v_mov_b32_e32 v102, v0
	v_mov_b32_e32 v103, v0
	v_mov_b32_e32 v104, v0
	v_mov_b32_e32 v105, v0
	v_mov_b32_e32 v106, v0
	v_mov_b32_e32 v107, v0
	v_mov_b32_e32 v108, v0
	v_mov_b32_e32 v109, v0
	v_mov_b32_e32 v110, v0
	v_mov_b32_e32 v111, v0
	v_mov_b32_e32 v112, v0
	v_mov_b32_e32 v113, v0
	v_mov_b32_e32 v114, v0
	v_mov_b32_e32 v115, v0
	v_mov_b32_e32 v116, v0
	v_mov_b32_e32 v117, v0
	v_mov_b32_e32 v118, v0
	v_mov_b32_e32 v119, v0
	v_mov_b32_e32 v120, v0
	v_mov_b32_e32 v121, v0
	v_mov_b32_e32 v122, v0
	v_mov_b32_e32 v123, v0
	v_mov_b32_e32 v124, v0
	v_mov_b32_e32 v125, v0
	v_mov_b32_e32 v126, v0
	v_mov_b32_e32 v127, v0
	s_branch .LBB0_912

.LBB0_919:
	s_or_b64 exec, exec, s[18:19]
	v_lshl_add_u32 v140, s20, 7, v128
	v_ashrrev_i32_e32 v141, 31, v140
	v_mad_i64_i32 v[138:139], s[18:19], v140, s37, 0
	v_mad_i64_i32 v[142:143], s[18:19], v140, s37, v[130:131]
	v_lshlrev_b64 v[140:141], 11, v[140:141]
	s_xor_b64 s[16:17], s[16:17], -1
	v_lshl_add_u64 v[144:145], v[132:133], 0, v[140:141]
	s_mov_b32 s18, 0
	global_load_dwordx4 v[206:209], v[142:143], off offset:-8
	v_lshl_add_u64 v[142:143], v[142:143], 0, s[12:13]
	global_load_dwordx4 v[210:213], v[142:143], off offset:-8
	v_lshl_add_u64 v[142:143], v[142:143], 0, s[12:13]
	global_load_dwordx4 v[214:217], v[142:143], off offset:-8
	v_lshl_add_u64 v[142:143], v[142:143], 0, s[12:13]
	global_load_dwordx4 v[218:221], v[142:143], off offset:-8
	v_lshl_add_u64 v[142:143], v[142:143], 0, s[12:13]
	v_mov_b32_e32 v142, v144
	v_mov_b32_e32 v143, v145
	global_load_dwordx4 v[222:225], v[142:143], off offset:-8
	v_lshl_add_u64 v[142:143], v[142:143], 0, s[14:15]
	global_load_dwordx4 v[226:229], v[142:143], off offset:-8
	v_lshl_add_u64 v[142:143], v[142:143], 0, s[14:15]
	global_load_dwordx4 v[246:249], v[142:143], off offset:-8
	v_lshl_add_u64 v[142:143], v[142:143], 0, s[14:15]
	global_load_dwordx4 v[250:253], v[142:143], off offset:-8
	s_waitcnt lgkmcnt(0)
	s_barrier
.LBB0_920:
	v_add_u32_e32 v176, s18, v175
	ds_read_b128 v[190:193], v176
	ds_read_b128 v[194:197], v176 offset:16
	s_add_i32 s18, s18, 0x8200
	s_cmp_lg_u32 s18, 0x20800
	s_waitcnt vmcnt(7)
	v_lshlrev_b32_e32 v176, 16, v206
	v_and_b32_e32 v177, 0xffff0000, v206
	v_lshlrev_b32_e32 v180, 16, v207
	v_and_b32_e32 v181, 0xffff0000, v207
	v_lshlrev_b32_e32 v182, 16, v208
	v_and_b32_e32 v183, 0xffff0000, v208
	v_lshlrev_b32_e32 v184, 16, v209
	v_and_b32_e32 v185, 0xffff0000, v209
	s_waitcnt vmcnt(3)
	v_lshlrev_b32_e32 v198, 16, v222
	v_and_b32_e32 v199, 0xffff0000, v222
	v_lshlrev_b32_e32 v186, 16, v223
	v_and_b32_e32 v187, 0xffff0000, v223
	v_lshlrev_b32_e32 v200, 16, v224
	v_and_b32_e32 v201, 0xffff0000, v224
	v_lshlrev_b32_e32 v188, 16, v225
	v_and_b32_e32 v189, 0xffff0000, v225
	s_waitcnt lgkmcnt(1)
	v_pk_fma_f32 v[176:177], v[190:191], v[176:177], v[198:199]
	v_pk_fma_f32 v[180:181], v[192:193], v[180:181], v[186:187]
	s_waitcnt lgkmcnt(0)
	v_pk_fma_f32 v[186:187], v[194:195], v[182:183], v[200:201]
	v_pk_fma_f32 v[188:189], v[196:197], v[184:185], v[188:189]
	v_cvt_pk_bf16_f32 v182, v176, v177
	v_cvt_pk_bf16_f32 v183, v180, v181
	v_cvt_pk_bf16_f32 v184, v186, v187
	v_cvt_pk_bf16_f32 v185, v188, v189
	global_store_dwordx4 v[144:145], v[182:185], off offset:-8
	v_lshl_add_u64 v[144:145], v[144:145], 0, s[14:15]
	v_add_u32_e32 v176, s18, v175
	ds_read_b128 v[190:193], v176
	ds_read_b128 v[194:197], v176 offset:16
	s_add_i32 s18, s18, 0x8200
	s_cmp_lg_u32 s18, 0x20800
	s_waitcnt vmcnt(7)
	v_lshlrev_b32_e32 v176, 16, v210
	v_and_b32_e32 v177, 0xffff0000, v210
	v_lshlrev_b32_e32 v180, 16, v211
	v_and_b32_e32 v181, 0xffff0000, v211
	v_lshlrev_b32_e32 v182, 16, v212
	v_and_b32_e32 v183, 0xffff0000, v212
	v_lshlrev_b32_e32 v184, 16, v213
	v_and_b32_e32 v185, 0xffff0000, v213
	s_waitcnt vmcnt(3)
	v_lshlrev_b32_e32 v198, 16, v226
	v_and_b32_e32 v199, 0xffff0000, v226
	v_lshlrev_b32_e32 v186, 16, v227
	v_and_b32_e32 v187, 0xffff0000, v227
	v_lshlrev_b32_e32 v200, 16, v228
	v_and_b32_e32 v201, 0xffff0000, v228
	v_lshlrev_b32_e32 v188, 16, v229
	v_and_b32_e32 v189, 0xffff0000, v229
	s_waitcnt lgkmcnt(1)
	v_pk_fma_f32 v[176:177], v[190:191], v[176:177], v[198:199]
	v_pk_fma_f32 v[180:181], v[192:193], v[180:181], v[186:187]
	s_waitcnt lgkmcnt(0)
	v_pk_fma_f32 v[186:187], v[194:195], v[182:183], v[200:201]
	v_pk_fma_f32 v[188:189], v[196:197], v[184:185], v[188:189]
	v_cvt_pk_bf16_f32 v182, v176, v177
	v_cvt_pk_bf16_f32 v183, v180, v181
	v_cvt_pk_bf16_f32 v184, v186, v187
	v_cvt_pk_bf16_f32 v185, v188, v189
	global_store_dwordx4 v[144:145], v[182:185], off offset:-8
	v_lshl_add_u64 v[144:145], v[144:145], 0, s[14:15]
	v_add_u32_e32 v176, s18, v175
	ds_read_b128 v[190:193], v176
	ds_read_b128 v[194:197], v176 offset:16
	s_add_i32 s18, s18, 0x8200
	s_cmp_lg_u32 s18, 0x20800
	s_waitcnt vmcnt(7)
	v_lshlrev_b32_e32 v176, 16, v214
	v_and_b32_e32 v177, 0xffff0000, v214
	v_lshlrev_b32_e32 v180, 16, v215
	v_and_b32_e32 v181, 0xffff0000, v215
	v_lshlrev_b32_e32 v182, 16, v216
	v_and_b32_e32 v183, 0xffff0000, v216
	v_lshlrev_b32_e32 v184, 16, v217
	v_and_b32_e32 v185, 0xffff0000, v217
	s_waitcnt vmcnt(3)
	v_lshlrev_b32_e32 v198, 16, v246
	v_and_b32_e32 v199, 0xffff0000, v246
	v_lshlrev_b32_e32 v186, 16, v247
	v_and_b32_e32 v187, 0xffff0000, v247
	v_lshlrev_b32_e32 v200, 16, v248
	v_and_b32_e32 v201, 0xffff0000, v248
	v_lshlrev_b32_e32 v188, 16, v249
	v_and_b32_e32 v189, 0xffff0000, v249
	s_waitcnt lgkmcnt(1)
	v_pk_fma_f32 v[176:177], v[190:191], v[176:177], v[198:199]
	v_pk_fma_f32 v[180:181], v[192:193], v[180:181], v[186:187]
	s_waitcnt lgkmcnt(0)
	v_pk_fma_f32 v[186:187], v[194:195], v[182:183], v[200:201]
	v_pk_fma_f32 v[188:189], v[196:197], v[184:185], v[188:189]
	v_cvt_pk_bf16_f32 v182, v176, v177
	v_cvt_pk_bf16_f32 v183, v180, v181
	v_cvt_pk_bf16_f32 v184, v186, v187
	v_cvt_pk_bf16_f32 v185, v188, v189
	global_store_dwordx4 v[144:145], v[182:185], off offset:-8
	v_lshl_add_u64 v[144:145], v[144:145], 0, s[14:15]
	v_add_u32_e32 v176, s18, v175
	ds_read_b128 v[190:193], v176
	ds_read_b128 v[194:197], v176 offset:16
	s_add_i32 s18, s18, 0x8200
	s_cmp_lg_u32 s18, 0x20800
	s_waitcnt vmcnt(7)
	v_lshlrev_b32_e32 v176, 16, v218
	v_and_b32_e32 v177, 0xffff0000, v218
	v_lshlrev_b32_e32 v180, 16, v219
	v_and_b32_e32 v181, 0xffff0000, v219
	v_lshlrev_b32_e32 v182, 16, v220
	v_and_b32_e32 v183, 0xffff0000, v220
	v_lshlrev_b32_e32 v184, 16, v221
	v_and_b32_e32 v185, 0xffff0000, v221
	s_waitcnt vmcnt(3)
	v_lshlrev_b32_e32 v198, 16, v250
	v_and_b32_e32 v199, 0xffff0000, v250
	v_lshlrev_b32_e32 v186, 16, v251
	v_and_b32_e32 v187, 0xffff0000, v251
	v_lshlrev_b32_e32 v200, 16, v252
	v_and_b32_e32 v201, 0xffff0000, v252
	v_lshlrev_b32_e32 v188, 16, v253
	v_and_b32_e32 v189, 0xffff0000, v253
	s_waitcnt lgkmcnt(1)
	v_pk_fma_f32 v[176:177], v[190:191], v[176:177], v[198:199]
	v_pk_fma_f32 v[180:181], v[192:193], v[180:181], v[186:187]
	s_waitcnt lgkmcnt(0)
	v_pk_fma_f32 v[186:187], v[194:195], v[182:183], v[200:201]
	v_pk_fma_f32 v[188:189], v[196:197], v[184:185], v[188:189]
	v_cvt_pk_bf16_f32 v182, v176, v177
	v_cvt_pk_bf16_f32 v183, v180, v181
	v_cvt_pk_bf16_f32 v184, v186, v187
	v_cvt_pk_bf16_f32 v185, v188, v189
	global_store_dwordx4 v[144:145], v[182:185], off offset:-8
	v_lshl_add_u64 v[144:145], v[144:145], 0, s[14:15]
	v_lshl_add_u64 v[138:139], v[134:135], 0, v[138:139]
	v_lshl_add_u64 v[140:141], v[136:137], 0, v[140:141]
	s_movk_i32 s18, 0x200
	global_load_dwordx4 v[206:209], v[138:139], off offset:-8
	v_lshl_add_u64 v[138:139], v[138:139], 0, s[12:13]
	global_load_dwordx4 v[210:213], v[138:139], off offset:-8
	v_lshl_add_u64 v[138:139], v[138:139], 0, s[12:13]
	global_load_dwordx4 v[214:217], v[138:139], off offset:-8
	v_lshl_add_u64 v[138:139], v[138:139], 0, s[12:13]
	global_load_dwordx4 v[218:221], v[138:139], off offset:-8
	v_lshl_add_u64 v[138:139], v[138:139], 0, s[12:13]
	v_mov_b32_e32 v138, v140
	v_mov_b32_e32 v139, v141
	global_load_dwordx4 v[222:225], v[138:139], off offset:-8
	v_lshl_add_u64 v[138:139], v[138:139], 0, s[14:15]
	global_load_dwordx4 v[226:229], v[138:139], off offset:-8
	v_lshl_add_u64 v[138:139], v[138:139], 0, s[14:15]
	global_load_dwordx4 v[246:249], v[138:139], off offset:-8
	v_lshl_add_u64 v[138:139], v[138:139], 0, s[14:15]
	global_load_dwordx4 v[250:253], v[138:139], off offset:-8
.LBB0_922:
	v_add_u32_e32 v176, s18, v175
	ds_read_b128 v[186:189], v176
	ds_read_b128 v[190:193], v176 offset:16
	s_add_i32 s18, s18, 0x8200
	s_cmp_lg_u32 s18, 0x20a00
	s_waitcnt vmcnt(7)
	v_lshlrev_b32_e32 v176, 16, v206
	v_and_b32_e32 v177, 0xffff0000, v206
	v_lshlrev_b32_e32 v142, 16, v207
	v_and_b32_e32 v143, 0xffff0000, v207
	v_lshlrev_b32_e32 v180, 16, v208
	v_and_b32_e32 v181, 0xffff0000, v208
	v_lshlrev_b32_e32 v144, 16, v209
	v_and_b32_e32 v145, 0xffff0000, v209
	s_waitcnt vmcnt(3)
	v_lshlrev_b32_e32 v194, 16, v222
	v_and_b32_e32 v195, 0xffff0000, v222
	v_lshlrev_b32_e32 v182, 16, v223
	v_and_b32_e32 v183, 0xffff0000, v223
	v_lshlrev_b32_e32 v196, 16, v224
	v_and_b32_e32 v197, 0xffff0000, v224
	v_lshlrev_b32_e32 v184, 16, v225
	v_and_b32_e32 v185, 0xffff0000, v225
	s_waitcnt lgkmcnt(1)
	v_pk_fma_f32 v[176:177], v[186:187], v[176:177], v[194:195]
	v_pk_fma_f32 v[182:183], v[188:189], v[142:143], v[182:183]
	s_waitcnt lgkmcnt(0)
	v_pk_fma_f32 v[180:181], v[190:191], v[180:181], v[196:197]
	v_pk_fma_f32 v[184:185], v[192:193], v[144:145], v[184:185]
	v_cvt_pk_bf16_f32 v142, v176, v177
	v_cvt_pk_bf16_f32 v143, v182, v183
	v_cvt_pk_bf16_f32 v144, v180, v181
	v_cvt_pk_bf16_f32 v145, v184, v185
	global_store_dwordx4 v[140:141], v[142:145], off offset:-8
	v_lshl_add_u64 v[140:141], v[140:141], 0, s[14:15]
	v_add_u32_e32 v176, s18, v175
	ds_read_b128 v[186:189], v176
	ds_read_b128 v[190:193], v176 offset:16
	s_add_i32 s18, s18, 0x8200
	s_cmp_lg_u32 s18, 0x20a00
	s_waitcnt vmcnt(7)
	v_lshlrev_b32_e32 v176, 16, v210
	v_and_b32_e32 v177, 0xffff0000, v210
	v_lshlrev_b32_e32 v142, 16, v211
	v_and_b32_e32 v143, 0xffff0000, v211
	v_lshlrev_b32_e32 v180, 16, v212
	v_and_b32_e32 v181, 0xffff0000, v212
	v_lshlrev_b32_e32 v144, 16, v213
	v_and_b32_e32 v145, 0xffff0000, v213
	s_waitcnt vmcnt(3)
	v_lshlrev_b32_e32 v194, 16, v226
	v_and_b32_e32 v195, 0xffff0000, v226
	v_lshlrev_b32_e32 v182, 16, v227
	v_and_b32_e32 v183, 0xffff0000, v227
	v_lshlrev_b32_e32 v196, 16, v228
	v_and_b32_e32 v197, 0xffff0000, v228
	v_lshlrev_b32_e32 v184, 16, v229
	v_and_b32_e32 v185, 0xffff0000, v229
	s_waitcnt lgkmcnt(1)
	v_pk_fma_f32 v[176:177], v[186:187], v[176:177], v[194:195]
	v_pk_fma_f32 v[182:183], v[188:189], v[142:143], v[182:183]
	s_waitcnt lgkmcnt(0)
	v_pk_fma_f32 v[180:181], v[190:191], v[180:181], v[196:197]
	v_pk_fma_f32 v[184:185], v[192:193], v[144:145], v[184:185]
	v_cvt_pk_bf16_f32 v142, v176, v177
	v_cvt_pk_bf16_f32 v143, v182, v183
	v_cvt_pk_bf16_f32 v144, v180, v181
	v_cvt_pk_bf16_f32 v145, v184, v185
	global_store_dwordx4 v[140:141], v[142:145], off offset:-8
	v_lshl_add_u64 v[140:141], v[140:141], 0, s[14:15]
	v_add_u32_e32 v176, s18, v175
	ds_read_b128 v[186:189], v176
	ds_read_b128 v[190:193], v176 offset:16
	s_add_i32 s18, s18, 0x8200
	s_cmp_lg_u32 s18, 0x20a00
	s_waitcnt vmcnt(7)
	v_lshlrev_b32_e32 v176, 16, v214
	v_and_b32_e32 v177, 0xffff0000, v214
	v_lshlrev_b32_e32 v142, 16, v215
	v_and_b32_e32 v143, 0xffff0000, v215
	v_lshlrev_b32_e32 v180, 16, v216
	v_and_b32_e32 v181, 0xffff0000, v216
	v_lshlrev_b32_e32 v144, 16, v217
	v_and_b32_e32 v145, 0xffff0000, v217
	s_waitcnt vmcnt(3)
	v_lshlrev_b32_e32 v194, 16, v246
	v_and_b32_e32 v195, 0xffff0000, v246
	v_lshlrev_b32_e32 v182, 16, v247
	v_and_b32_e32 v183, 0xffff0000, v247
	v_lshlrev_b32_e32 v196, 16, v248
	v_and_b32_e32 v197, 0xffff0000, v248
	v_lshlrev_b32_e32 v184, 16, v249
	v_and_b32_e32 v185, 0xffff0000, v249
	s_waitcnt lgkmcnt(1)
	v_pk_fma_f32 v[176:177], v[186:187], v[176:177], v[194:195]
	v_pk_fma_f32 v[182:183], v[188:189], v[142:143], v[182:183]
	s_waitcnt lgkmcnt(0)
	v_pk_fma_f32 v[180:181], v[190:191], v[180:181], v[196:197]
	v_pk_fma_f32 v[184:185], v[192:193], v[144:145], v[184:185]
	v_cvt_pk_bf16_f32 v142, v176, v177
	v_cvt_pk_bf16_f32 v143, v182, v183
	v_cvt_pk_bf16_f32 v144, v180, v181
	v_cvt_pk_bf16_f32 v145, v184, v185
	global_store_dwordx4 v[140:141], v[142:145], off offset:-8
	v_lshl_add_u64 v[140:141], v[140:141], 0, s[14:15]
	v_add_u32_e32 v176, s18, v175
	ds_read_b128 v[186:189], v176
	ds_read_b128 v[190:193], v176 offset:16
	s_add_i32 s18, s18, 0x8200
	s_cmp_lg_u32 s18, 0x20a00
	s_waitcnt vmcnt(7)
	v_lshlrev_b32_e32 v176, 16, v218
	v_and_b32_e32 v177, 0xffff0000, v218
	v_lshlrev_b32_e32 v142, 16, v219
	v_and_b32_e32 v143, 0xffff0000, v219
	v_lshlrev_b32_e32 v180, 16, v220
	v_and_b32_e32 v181, 0xffff0000, v220
	v_lshlrev_b32_e32 v144, 16, v221
	v_and_b32_e32 v145, 0xffff0000, v221
	s_waitcnt vmcnt(3)
	v_lshlrev_b32_e32 v194, 16, v250
	v_and_b32_e32 v195, 0xffff0000, v250
	v_lshlrev_b32_e32 v182, 16, v251
	v_and_b32_e32 v183, 0xffff0000, v251
	v_lshlrev_b32_e32 v196, 16, v252
	v_and_b32_e32 v197, 0xffff0000, v252
	v_lshlrev_b32_e32 v184, 16, v253
	v_and_b32_e32 v185, 0xffff0000, v253
	s_waitcnt lgkmcnt(1)
	v_pk_fma_f32 v[176:177], v[186:187], v[176:177], v[194:195]
	v_pk_fma_f32 v[182:183], v[188:189], v[142:143], v[182:183]
	s_waitcnt lgkmcnt(0)
	v_pk_fma_f32 v[180:181], v[190:191], v[180:181], v[196:197]
	v_pk_fma_f32 v[184:185], v[192:193], v[144:145], v[184:185]
	v_cvt_pk_bf16_f32 v142, v176, v177
	v_cvt_pk_bf16_f32 v143, v182, v183
	v_cvt_pk_bf16_f32 v144, v180, v181
	v_cvt_pk_bf16_f32 v145, v184, v185
	global_store_dwordx4 v[140:141], v[142:145], off offset:-8
	v_lshl_add_u64 v[140:141], v[140:141], 0, s[14:15]
	s_mov_b32 s20, 1
	s_andn2_b64 vcc, exec, s[16:17]
	s_mov_b64 s[16:17], 0
	s_cbranch_vccnz .LBB0_917
	s_add_i32 s39, s39, s90
	s_add_i32 s34, s34, s35
	s_add_i32 s38, s38, s84
	s_cmpk_lt_i32 s39, 0x100
	s_cbranch_scc1 .LBB0_896
